# base16 + LN2 preamble: 16 staging loads in flight together, one wait, then the 8 LDS writes
# baseline (speedup 1.0000x reference)
; __device__ __forceinline__ void phase_ln2(const Args& a, LAS unsigned char* lds, const WCtx& w, int l, int nrows) {
;     ...
;     for (int i = w.tid; i < 1024; i += NTHREADS) { LNG[i] = a.in[I_LN2G][l * 1024 + i]; LNB[i] = a.in[I_LN2B][l * 1024 + i];
; #pragma unroll
;         for (int s = 0; s < 2; ++s) { const int bb = s ? b_hi : b_lo; const float* mp = (const float*)(a.ws + WS_MOD) + (size_t)(l * 17 + bb) * 6144; const float* mn = (const float*)(a.ws + WS_MOD) + (size_t)(ln * 17 + bb) * 6144;
;             BV[(s * 3 + 0) * 1024 + i] = mp[5120 + i]; BV[(s * 3 + 1) * 1024 + i] = mn[i]; BV[(s * 3 + 2) * 1024 + i] = mn[1024 + i]; } }
.LBB0_2545:
	v_add_u32_e32 v8, s29, v2
	v_add_u32_e32 v10, s30, v3
	v_ashrrev_i32_e32 v9, 31, v8
	v_ashrrev_i32_e32 v11, 31, v10
	v_lshlrev_b64 v[8:9], 2, v[8:9]
	v_lshl_add_u64 v[12:13], s[66:67], 0, v[8:9]
	v_lshlrev_b64 v[10:11], 2, v[10:11]
	v_lshl_add_u64 v[14:15], s[66:67], 0, v[10:11]
	global_load_dword v21, v[12:13], off
	global_load_dword v22, v[14:15], off
	v_lshl_add_u64 v[8:9], s[68:69], 0, v[8:9]
	v_lshl_add_u64 v[10:11], s[68:69], 0, v[10:11]
	v_ashrrev_i32_e32 v15, 31, v2
	v_mov_b32_e32 v14, v2
	v_ashrrev_i32_e32 v13, 31, v3
	v_mov_b32_e32 v12, v3
	v_add_u32_e32 v7, -2, v7
	v_add_u32_e32 v3, 0x400, v3
	v_add_u32_e32 v2, 0x400, v2
	global_load_dword v23, v[8:9], off
	s_nop 0
	global_load_dword v24, v[10:11], off
	v_lshl_add_u64 v[10:11], v[12:13], 2, s[34:35]
	v_add_u32_e32 v16, 0x1000, v4
	v_lshl_add_u64 v[8:9], v[14:15], 2, s[34:35]
	v_lshl_add_u64 v[12:13], v[8:9], 0, s[4:5]
	v_add_co_u32_e32 v12, vcc, s38, v12
	v_lshl_add_u64 v[14:15], v[10:11], 0, s[4:5]
	s_nop 0
	v_addc_co_u32_e32 v13, vcc, 0, v13, vcc
	global_load_dword v25, v[12:13], off
	v_add_co_u32_e32 v12, vcc, s38, v14
	s_nop 1
	v_addc_co_u32_e32 v13, vcc, 0, v15, vcc
	global_load_dword v26, v[12:13], off
	v_lshl_add_u64 v[14:15], v[10:11], 0, s[12:13]
	v_lshl_add_u64 v[12:13], v[8:9], 0, s[12:13]
	global_load_dword v27, v[12:13], off
	global_load_dword v28, v[14:15], off
	v_add_co_u32_e32 v12, vcc, s22, v12
	v_addc_co_u32_e32 v13, vcc, 0, v13, vcc
	global_load_dword v29, v[12:13], off
	v_add_co_u32_e32 v12, vcc, s22, v14
	s_nop 1
	v_addc_co_u32_e32 v13, vcc, 0, v15, vcc
	global_load_dword v30, v[12:13], off
	v_lshl_add_u64 v[14:15], v[10:11], 0, s[6:7]
	v_lshl_add_u64 v[10:11], v[10:11], 0, s[10:11]
	v_lshl_add_u64 v[12:13], v[8:9], 0, s[6:7]
	v_add_co_u32_e32 v12, vcc, s38, v12
	v_lshl_add_u64 v[8:9], v[8:9], 0, s[10:11]
	s_nop 0
	v_addc_co_u32_e32 v13, vcc, 0, v13, vcc
	global_load_dword v31, v[12:13], off
	v_add_co_u32_e32 v12, vcc, s38, v14
	s_nop 1
	v_addc_co_u32_e32 v13, vcc, 0, v15, vcc
	global_load_dword v32, v[12:13], off
	global_load_dword v33, v[8:9], off
	global_load_dword v36, v[10:11], off
	v_add_co_u32_e32 v8, vcc, s22, v8
	v_addc_co_u32_e32 v9, vcc, 0, v9, vcc
	global_load_dword v37, v[8:9], off
	v_add_co_u32_e32 v8, vcc, 0x1000, v10
	s_nop 1
	v_addc_co_u32_e32 v9, vcc, 0, v11, vcc
	global_load_dword v38, v[8:9], off
	v_cmp_eq_u32_e32 vcc, 0, v7
	s_or_b64 s[8:9], vcc, s[8:9]
	s_waitcnt vmcnt(0)
	ds_write2st64_b32 v4, v21, v22 offset1:8
	ds_write2st64_b32 v4, v23, v24 offset0:16 offset1:24
	ds_write2st64_b32 v4, v25, v26 offset0:32 offset1:40
	ds_write2st64_b32 v4, v27, v28 offset0:48 offset1:56
	ds_write2st64_b32 v4, v29, v30 offset0:64 offset1:72
	ds_write2st64_b32 v4, v31, v32 offset0:80 offset1:88
	ds_write2st64_b32 v4, v33, v36 offset0:96 offset1:104
	ds_write2st64_b32 v4, v37, v38 offset0:112 offset1:120
	v_mov_b32_e32 v4, v16
	s_andn2_b64 exec, exec, s[8:9]
	s_cbranch_execnz .LBB0_2545
	s_or_b64 exec, exec, s[8:9]
	v_cmp_ne_u32_e32 vcc, v5, v6
	v_readlane_b32 s60, v255, 2
	s_mov_b32 s58, 0x3f6c835e
	v_lshl_add_u32 v2, v6, 9, v34
	s_orn2_b64 s[4:5], vcc, exec
	v_readlane_b32 s61, v255, 3
	s_mov_b32 s59, 0xbec3ef15
	s_movk_i32 s70, 0x4000
	s_mov_b32 s69, 0x7f800000
	s_movk_i32 s71, 0x1ff
	s_movk_i32 s68, 0x2200
	v_readlane_b32 s62, v255, 4
	s_mov_b32 s63, 0xbf6c835e
	s_movk_i32 s64, 0x440
